# G1 rot/plain epilogue stores written through (sc0 sc1) to leave fewer dirty L2 lines for the grid barrier's writeback
# baseline (speedup 1.0000x reference)
; __device__ __forceinline__ unsigned cvt_pk_bf16(float lo, float hi) { unsigned r; asm volatile("v_cvt_pk_bf16_f32 %0, %1, %2" : "=v"(r) : "v"(lo), "v"(hi)); return r; }
;     __device__ __forceinline__ void operator()(AccT& acc, const Unit& u, int wr, int wc, int fr, int fq) const {
;     ...
; #pragma unroll
;         for (int ai = 0; ai < 2; ++ai)
; #pragma unroll
;             for (int m = 0; m < 4; ++m) { const int row = row0 + ai * 128 + m * 16; bf16_t* rowp = O + (size_t)row * NPROJ + col0;
;                 f32x4 cs0 = (f32x4){1.f, 0.f, 1.f, 0.f}, cs1 = cs0;
;                 if (rot) { const int pos = row < HALF_TOK ? (row & 8191) : ((row - HALF_TOK) & 2047); const f32x2* rp = rope + (size_t)pos * 64 + i0; cs0 = *(const f32x4*)rp; cs1 = *(const f32x4*)(rp + 2); }
; #pragma unroll
;                 for (int bj = 0; bj < 2; ++bj) { f32x4 v0 = acc[ai][bj][m][0], v1 = acc[ai][bj][m][1];
;                     if (rot) { const f32x4 a = v0, b = v1;
;                         v0[0] = a[0] * cs0[0] - a[1] * cs0[1]; v0[1] = a[1] * cs0[0] + a[0] * cs0[1]; v0[2] = a[2] * cs0[2] - a[3] * cs0[3]; v0[3] = a[3] * cs0[2] + a[2] * cs0[3];
;                         v1[0] = b[0] * cs1[0] - b[1] * cs1[1]; v1[1] = b[1] * cs1[0] + b[0] * cs1[1]; v1[2] = b[2] * cs1[2] - b[3] * cs1[3]; v1[3] = b[3] * cs1[2] + b[2] * cs1[3]; }
;                     u32x4 w; w.x = cvt_pk_bf16(v0[0], v0[1]); w.y = cvt_pk_bf16(v0[2], v0[3]); w.z = cvt_pk_bf16(v1[0], v1[1]); w.w = cvt_pk_bf16(v1[2], v1[3]);
;                     *(u32x4*)(rowp + bj * 128) = w; }
;                 __builtin_amdgcn_sched_barrier(0); }
.LBB0_614:
	s_lshl_b32 s2, s24, 8
	v_mov_b32_e32 v190, v169
	v_mov_b32_e32 v0, v187
	s_or_b32 s2, s2, s52
	s_nop 0
	v_lshl_add_u32 v158, v0, 3, s2
	s_and_b32 s2, s24, -4
	s_cmp_eq_u32 s2, 8
	s_mov_b64 s[2:3], -1
	s_cbranch_scc1 .LBB0_680
	s_lshl_b32 s2, s0, 8
	s_add_i32 s2, s2, s38
	v_add_u32_e32 v140, s2, v190
	v_ashrrev_i32_e32 v159, 31, v158
	v_ashrrev_i32_e32 v141, 31, v140
	v_lshlrev_b64 v[142:143], 13, v[140:141]
	v_lshl_add_u64 v[142:143], s[22:23], 0, v[142:143]
	v_lshl_add_u64 v[142:143], v[158:159], 1, v[142:143]
	s_mov_b32 s2, 0x20000
	s_mov_b32 s3, 0
	s_cmp_lt_i32 s24, 4
	s_cbranch_scc1 .Lg1_rot
	v_cvt_pk_bf16_f32 v164, v126, v127
	v_cvt_pk_bf16_f32 v165, v128, v129
	v_cvt_pk_bf16_f32 v166, v110, v111
	v_cvt_pk_bf16_f32 v167, v112, v113
	global_store_dwordx4 v[142:143], v[164:167], off sc0 sc1
	v_cvt_pk_bf16_f32 v178, v94, v95
	v_cvt_pk_bf16_f32 v179, v96, v97
	v_cvt_pk_bf16_f32 v180, v78, v79
	v_cvt_pk_bf16_f32 v181, v80, v81
	global_store_dwordx4 v[142:143], v[178:181], off offset:256 sc0 sc1
	v_lshl_add_u64 v[144:145], v[142:143], 0, s[2:3]
	v_cvt_pk_bf16_f32 v164, v122, v123
	v_cvt_pk_bf16_f32 v165, v124, v125
	v_cvt_pk_bf16_f32 v166, v106, v107
	v_cvt_pk_bf16_f32 v167, v108, v109
	global_store_dwordx4 v[144:145], v[164:167], off sc0 sc1
	v_cvt_pk_bf16_f32 v178, v90, v91
	v_cvt_pk_bf16_f32 v179, v92, v93
	v_cvt_pk_bf16_f32 v180, v74, v75
	v_cvt_pk_bf16_f32 v181, v76, v77
	global_store_dwordx4 v[144:145], v[178:181], off offset:256 sc0 sc1
	v_lshl_add_u64 v[142:143], v[144:145], 0, s[2:3]
	v_cvt_pk_bf16_f32 v164, v118, v119
	v_cvt_pk_bf16_f32 v165, v120, v121
	v_cvt_pk_bf16_f32 v166, v102, v103
	v_cvt_pk_bf16_f32 v167, v104, v105
	global_store_dwordx4 v[142:143], v[164:167], off sc0 sc1
	v_cvt_pk_bf16_f32 v178, v86, v87
	v_cvt_pk_bf16_f32 v179, v88, v89
	v_cvt_pk_bf16_f32 v180, v70, v71
	v_cvt_pk_bf16_f32 v181, v72, v73
	global_store_dwordx4 v[142:143], v[178:181], off offset:256 sc0 sc1
	v_lshl_add_u64 v[144:145], v[142:143], 0, s[2:3]
	v_cvt_pk_bf16_f32 v164, v114, v115
	v_cvt_pk_bf16_f32 v165, v116, v117
	v_cvt_pk_bf16_f32 v166, v98, v99
	v_cvt_pk_bf16_f32 v167, v100, v101
	global_store_dwordx4 v[144:145], v[164:167], off sc0 sc1
	v_cvt_pk_bf16_f32 v178, v82, v83
	v_cvt_pk_bf16_f32 v179, v84, v85
	v_cvt_pk_bf16_f32 v180, v66, v67
	v_cvt_pk_bf16_f32 v181, v68, v69
	global_store_dwordx4 v[144:145], v[178:181], off offset:256 sc0 sc1
	v_lshl_add_u64 v[142:143], v[144:145], 0, s[2:3]
	v_lshl_add_u64 v[142:143], v[142:143], 0, s[2:3]
	v_lshl_add_u64 v[142:143], v[142:143], 0, s[2:3]
	v_lshl_add_u64 v[142:143], v[142:143], 0, s[2:3]
	v_lshl_add_u64 v[142:143], v[142:143], 0, s[2:3]
	v_cvt_pk_bf16_f32 v164, v62, v63
	v_cvt_pk_bf16_f32 v165, v64, v65
	v_cvt_pk_bf16_f32 v166, v46, v47
	v_cvt_pk_bf16_f32 v167, v48, v49
	global_store_dwordx4 v[142:143], v[164:167], off sc0 sc1
	v_cvt_pk_bf16_f32 v178, v30, v31
	v_cvt_pk_bf16_f32 v179, v32, v33
	v_cvt_pk_bf16_f32 v180, v14, v15
	v_cvt_pk_bf16_f32 v181, v16, v17
	global_store_dwordx4 v[142:143], v[178:181], off offset:256 sc0 sc1
	v_lshl_add_u64 v[144:145], v[142:143], 0, s[2:3]
	v_cvt_pk_bf16_f32 v164, v58, v59
	v_cvt_pk_bf16_f32 v165, v60, v61
	v_cvt_pk_bf16_f32 v166, v42, v43
	v_cvt_pk_bf16_f32 v167, v44, v45
	global_store_dwordx4 v[144:145], v[164:167], off sc0 sc1
	v_cvt_pk_bf16_f32 v178, v26, v27
	v_cvt_pk_bf16_f32 v179, v28, v29
	v_cvt_pk_bf16_f32 v180, v10, v11
	v_cvt_pk_bf16_f32 v181, v12, v13
	global_store_dwordx4 v[144:145], v[178:181], off offset:256 sc0 sc1
	v_lshl_add_u64 v[142:143], v[144:145], 0, s[2:3]
	v_cvt_pk_bf16_f32 v164, v54, v55
	v_cvt_pk_bf16_f32 v165, v56, v57
	v_cvt_pk_bf16_f32 v166, v38, v39
	v_cvt_pk_bf16_f32 v167, v40, v41
	global_store_dwordx4 v[142:143], v[164:167], off sc0 sc1
	v_cvt_pk_bf16_f32 v178, v22, v23
	v_cvt_pk_bf16_f32 v179, v24, v25
	v_cvt_pk_bf16_f32 v180, v6, v7
	v_cvt_pk_bf16_f32 v181, v8, v9
	global_store_dwordx4 v[142:143], v[178:181], off offset:256 sc0 sc1
	v_lshl_add_u64 v[144:145], v[142:143], 0, s[2:3]
	v_cvt_pk_bf16_f32 v164, v50, v51
	v_cvt_pk_bf16_f32 v165, v52, v53
	v_cvt_pk_bf16_f32 v166, v34, v35
	v_cvt_pk_bf16_f32 v167, v36, v37
	global_store_dwordx4 v[144:145], v[164:167], off sc0 sc1
	v_cvt_pk_bf16_f32 v178, v18, v19
	v_cvt_pk_bf16_f32 v179, v20, v21
	v_cvt_pk_bf16_f32 v180, v2, v3
	v_cvt_pk_bf16_f32 v181, v4, v5
	global_store_dwordx4 v[144:145], v[178:181], off offset:256 sc0 sc1
	s_branch .Lg1_epi_done
;     __device__ __forceinline__ void operator()(AccT& acc, const Unit& u, int wr, int wc, int fr, int fq) const {
;     ...
;             for (int m = 0; m < 4; ++m) { const int row = row0 + ai * 128 + m * 16; bf16_t* rowp = O + (size_t)row * NPROJ + col0;
;                 f32x4 cs0 = (f32x4){1.f, 0.f, 1.f, 0.f}, cs1 = cs0;
;                 if (rot) { const int pos = row < HALF_TOK ? (row & 8191) : ((row - HALF_TOK) & 2047); const f32x2* rp = rope + (size_t)pos * 64 + i0; cs0 = *(const f32x4*)rp; cs1 = *(const f32x4*)(rp + 2); }
; #pragma unroll
;                 for (int bj = 0; bj < 2; ++bj) { f32x4 v0 = acc[ai][bj][m][0], v1 = acc[ai][bj][m][1];
;                     if (rot) { const f32x4 a = v0, b = v1;
;                         v0[0] = a[0] * cs0[0] - a[1] * cs0[1]; v0[1] = a[1] * cs0[0] + a[0] * cs0[1]; v0[2] = a[2] * cs0[2] - a[3] * cs0[3]; v0[3] = a[3] * cs0[2] + a[2] * cs0[3];
;                         v1[0] = b[0] * cs1[0] - b[1] * cs1[1]; v1[1] = b[1] * cs1[0] + b[0] * cs1[1]; v1[2] = b[2] * cs1[2] - b[3] * cs1[3]; v1[3] = b[3] * cs1[2] + b[2] * cs1[3]; }
.Lg1_rot:
	s_movk_i32 s4, 0x4000
	v_lshl_add_u32 v138, v0, 2, s79
	v_cmp_gt_i32_e32 vcc, s4, v140
	v_mov_b32_e32 v0, 0x7ff
	v_mov_b32_e32 v160, 0x1fff
	v_ashrrev_i32_e32 v139, 31, v138
	v_cndmask_b32_e32 v0, v0, v160, vcc
	v_and_b32_e32 v0, v0, v140
	v_lshlrev_b32_e32 v0, 9, v0
	v_lshl_add_u64 v[160:161], s[46:47], 0, v[0:1]
	v_lshl_add_u64 v[138:139], v[138:139], 3, v[160:161]
	s_mov_b32 s42, 0x2000
	s_mov_b32 s43, 0
	global_load_dwordx4 v[134:137], v[138:139], off
	global_load_dwordx4 v[130:133], v[138:139], off offset:16
	s_nop 0
	v_lshl_add_u64 v[138:139], v[138:139], 0, s[42:43]
	global_load_dwordx4 v[182:185], v[138:139], off
	global_load_dwordx4 v[192:195], v[138:139], off offset:16
	s_nop 0
	v_lshl_add_u64 v[138:139], v[138:139], 0, s[42:43]
	global_load_dwordx4 v[196:199], v[138:139], off
	global_load_dwordx4 v[204:207], v[138:139], off offset:16
	s_nop 0
	v_lshl_add_u64 v[138:139], v[138:139], 0, s[42:43]
	global_load_dwordx4 v[222:225], v[138:139], off
	global_load_dwordx4 v[226:229], v[138:139], off offset:16
	s_nop 0
	v_lshl_add_u64 v[138:139], v[138:139], 0, s[42:43]
	v_lshl_add_u64 v[138:139], v[138:139], 0, s[42:43]
	v_lshl_add_u64 v[138:139], v[138:139], 0, s[42:43]
	v_lshl_add_u64 v[138:139], v[138:139], 0, s[42:43]
	v_lshl_add_u64 v[138:139], v[138:139], 0, s[42:43]
	s_waitcnt vmcnt(6)
	v_mul_f32_e32 v0, v127, v135
	v_mul_f32_e32 v172, v111, v131
	v_mul_f32_e32 v160, v126, v135
	v_mul_f32_e32 v173, v110, v131
	v_mul_f32_e32 v161, v126, v134
	v_mul_f32_e32 v174, v110, v130
	v_mul_f32_e32 v170, v137, v129
	v_mul_f32_e32 v175, v133, v113
	v_mul_f32_e32 v171, v128, v137
	v_mul_f32_e32 v176, v112, v133
	v_fma_f32 v127, v127, v134, v160
	v_fma_f32 v111, v111, v130, v173
	v_sub_f32_e32 v126, v161, v0
	v_sub_f32_e32 v110, v174, v172
	v_fma_f32 v128, v136, v128, -v170
	v_fma_f32 v112, v132, v112, -v175
	v_fma_f32 v129, v129, v136, v171
	v_fma_f32 v113, v113, v132, v176
	v_mul_f32_e32 v0, v95, v135
	v_mul_f32_e32 v172, v79, v131
	v_mul_f32_e32 v160, v94, v135
	v_mul_f32_e32 v173, v78, v131
	v_mul_f32_e32 v161, v94, v134
	v_mul_f32_e32 v174, v78, v130
	v_mul_f32_e32 v170, v137, v97
	v_mul_f32_e32 v175, v133, v81
	v_mul_f32_e32 v171, v96, v137
	v_mul_f32_e32 v176, v80, v133
	v_fma_f32 v95, v95, v134, v160
	v_fma_f32 v79, v79, v130, v173
	v_sub_f32_e32 v94, v161, v0
	v_sub_f32_e32 v78, v174, v172
	v_fma_f32 v96, v136, v96, -v170
	v_fma_f32 v80, v132, v80, -v175
	v_fma_f32 v97, v97, v136, v171
	v_fma_f32 v81, v81, v132, v176
	global_load_dwordx4 v[134:137], v[138:139], off
	global_load_dwordx4 v[130:133], v[138:139], off offset:16
	s_nop 0
	v_lshl_add_u64 v[138:139], v[138:139], 0, s[42:43]
	s_waitcnt vmcnt(6)
	v_mul_f32_e32 v0, v123, v183
	v_mul_f32_e32 v172, v107, v193
	v_mul_f32_e32 v160, v122, v183
	v_mul_f32_e32 v173, v106, v193
	v_mul_f32_e32 v161, v122, v182
	v_mul_f32_e32 v174, v106, v192
	v_mul_f32_e32 v170, v185, v125
	v_mul_f32_e32 v175, v195, v109
	v_mul_f32_e32 v171, v124, v185
	v_mul_f32_e32 v176, v108, v195
	v_fma_f32 v123, v123, v182, v160
	v_fma_f32 v107, v107, v192, v173
	v_sub_f32_e32 v122, v161, v0
	v_sub_f32_e32 v106, v174, v172
	v_fma_f32 v124, v184, v124, -v170
	v_fma_f32 v108, v194, v108, -v175
	v_fma_f32 v125, v125, v184, v171
	v_fma_f32 v109, v109, v194, v176
	v_mul_f32_e32 v0, v91, v183
	v_mul_f32_e32 v172, v75, v193
	v_mul_f32_e32 v160, v90, v183
	v_mul_f32_e32 v173, v74, v193
	v_mul_f32_e32 v161, v90, v182
	v_mul_f32_e32 v174, v74, v192
	v_mul_f32_e32 v170, v185, v93
	v_mul_f32_e32 v175, v195, v77
	v_mul_f32_e32 v171, v92, v185
	v_mul_f32_e32 v176, v76, v195
	v_fma_f32 v91, v91, v182, v160
	v_fma_f32 v75, v75, v192, v173
	v_sub_f32_e32 v90, v161, v0
	v_sub_f32_e32 v74, v174, v172
	v_fma_f32 v92, v184, v92, -v170
	v_fma_f32 v76, v194, v76, -v175
	v_fma_f32 v93, v93, v184, v171
	v_fma_f32 v77, v77, v194, v176
	global_load_dwordx4 v[182:185], v[138:139], off
	global_load_dwordx4 v[192:195], v[138:139], off offset:16
	s_nop 0
	v_lshl_add_u64 v[138:139], v[138:139], 0, s[42:43]
	s_waitcnt vmcnt(6)
	v_mul_f32_e32 v0, v119, v197
	v_mul_f32_e32 v172, v103, v205
	v_mul_f32_e32 v160, v118, v197
	v_mul_f32_e32 v173, v102, v205
	v_mul_f32_e32 v161, v118, v196
	v_mul_f32_e32 v174, v102, v204
	v_mul_f32_e32 v170, v199, v121
	v_mul_f32_e32 v175, v207, v105
	v_mul_f32_e32 v171, v120, v199
	v_mul_f32_e32 v176, v104, v207
	v_fma_f32 v119, v119, v196, v160
	v_fma_f32 v103, v103, v204, v173
	v_sub_f32_e32 v118, v161, v0
	v_sub_f32_e32 v102, v174, v172
	v_fma_f32 v120, v198, v120, -v170
	v_fma_f32 v104, v206, v104, -v175
	v_fma_f32 v121, v121, v198, v171
	v_fma_f32 v105, v105, v206, v176
	v_mul_f32_e32 v0, v87, v197
	v_mul_f32_e32 v172, v71, v205
	v_mul_f32_e32 v160, v86, v197
	v_mul_f32_e32 v173, v70, v205
	v_mul_f32_e32 v161, v86, v196
	v_mul_f32_e32 v174, v70, v204
	v_mul_f32_e32 v170, v199, v89
	v_mul_f32_e32 v175, v207, v73
	v_mul_f32_e32 v171, v88, v199
	v_mul_f32_e32 v176, v72, v207
	v_fma_f32 v87, v87, v196, v160
	v_fma_f32 v71, v71, v204, v173
	v_sub_f32_e32 v86, v161, v0
	v_sub_f32_e32 v70, v174, v172
	v_fma_f32 v88, v198, v88, -v170
	v_fma_f32 v72, v206, v72, -v175
	v_fma_f32 v89, v89, v198, v171
	v_fma_f32 v73, v73, v206, v176
	global_load_dwordx4 v[196:199], v[138:139], off
	global_load_dwordx4 v[204:207], v[138:139], off offset:16
	s_nop 0
	v_lshl_add_u64 v[138:139], v[138:139], 0, s[42:43]
	s_waitcnt vmcnt(6)
;     __device__ __forceinline__ void operator()(AccT& acc, const Unit& u, int wr, int wc, int fr, int fq) const {
;     ...
;                     if (rot) { const f32x4 a = v0, b = v1;
;                         v0[0] = a[0] * cs0[0] - a[1] * cs0[1]; v0[1] = a[1] * cs0[0] + a[0] * cs0[1]; v0[2] = a[2] * cs0[2] - a[3] * cs0[3]; v0[3] = a[3] * cs0[2] + a[2] * cs0[3];
;                         v1[0] = b[0] * cs1[0] - b[1] * cs1[1]; v1[1] = b[1] * cs1[0] + b[0] * cs1[1]; v1[2] = b[2] * cs1[2] - b[3] * cs1[3]; v1[3] = b[3] * cs1[2] + b[2] * cs1[3]; }
	v_mul_f32_e32 v0, v115, v223
	v_mul_f32_e32 v172, v99, v227
	v_mul_f32_e32 v160, v114, v223
	v_mul_f32_e32 v173, v98, v227
	v_mul_f32_e32 v161, v114, v222
	v_mul_f32_e32 v174, v98, v226
	v_mul_f32_e32 v170, v225, v117
	v_mul_f32_e32 v175, v229, v101
	v_mul_f32_e32 v171, v116, v225
	v_mul_f32_e32 v176, v100, v229
	v_fma_f32 v115, v115, v222, v160
	v_fma_f32 v99, v99, v226, v173
	v_sub_f32_e32 v114, v161, v0
	v_sub_f32_e32 v98, v174, v172
	v_fma_f32 v116, v224, v116, -v170
	v_fma_f32 v100, v228, v100, -v175
	v_fma_f32 v117, v117, v224, v171
	v_fma_f32 v101, v101, v228, v176
	v_mul_f32_e32 v0, v83, v223
	v_mul_f32_e32 v172, v67, v227
	v_mul_f32_e32 v160, v82, v223
	v_mul_f32_e32 v173, v66, v227
	v_mul_f32_e32 v161, v82, v222
	v_mul_f32_e32 v174, v66, v226
	v_mul_f32_e32 v170, v225, v85
	v_mul_f32_e32 v175, v229, v69
	v_mul_f32_e32 v171, v84, v225
	v_mul_f32_e32 v176, v68, v229
	v_fma_f32 v83, v83, v222, v160
	v_fma_f32 v67, v67, v226, v173
	v_sub_f32_e32 v82, v161, v0
	v_sub_f32_e32 v66, v174, v172
	v_fma_f32 v84, v224, v84, -v170
	v_fma_f32 v68, v228, v68, -v175
	v_fma_f32 v85, v85, v224, v171
	v_fma_f32 v69, v69, v228, v176
	global_load_dwordx4 v[222:225], v[138:139], off
	global_load_dwordx4 v[226:229], v[138:139], off offset:16
	s_waitcnt vmcnt(6)
	v_mul_f32_e32 v0, v63, v135
	v_mul_f32_e32 v172, v47, v131
	v_mul_f32_e32 v160, v62, v135
	v_mul_f32_e32 v173, v46, v131
	v_mul_f32_e32 v161, v62, v134
	v_mul_f32_e32 v174, v46, v130
	v_mul_f32_e32 v170, v137, v65
	v_mul_f32_e32 v175, v133, v49
	v_mul_f32_e32 v171, v64, v137
	v_mul_f32_e32 v176, v48, v133
	v_fma_f32 v63, v63, v134, v160
	v_fma_f32 v47, v47, v130, v173
	v_sub_f32_e32 v62, v161, v0
	v_sub_f32_e32 v46, v174, v172
	v_fma_f32 v64, v136, v64, -v170
	v_fma_f32 v48, v132, v48, -v175
	v_fma_f32 v65, v65, v136, v171
	v_fma_f32 v49, v49, v132, v176
	v_mul_f32_e32 v0, v31, v135
	v_mul_f32_e32 v172, v15, v131
	v_mul_f32_e32 v160, v30, v135
	v_mul_f32_e32 v173, v14, v131
	v_mul_f32_e32 v161, v30, v134
	v_mul_f32_e32 v174, v14, v130
	v_mul_f32_e32 v170, v137, v33
	v_mul_f32_e32 v175, v133, v17
	v_mul_f32_e32 v171, v32, v137
	v_mul_f32_e32 v176, v16, v133
	v_fma_f32 v31, v31, v134, v160
	v_fma_f32 v15, v15, v130, v173
	v_sub_f32_e32 v30, v161, v0
	v_sub_f32_e32 v14, v174, v172
	v_fma_f32 v32, v136, v32, -v170
	v_fma_f32 v16, v132, v16, -v175
	v_fma_f32 v33, v33, v136, v171
	v_fma_f32 v17, v17, v132, v176
	s_waitcnt vmcnt(4)
	v_mul_f32_e32 v0, v59, v183
	v_mul_f32_e32 v172, v43, v193
	v_mul_f32_e32 v160, v58, v183
	v_mul_f32_e32 v173, v42, v193
	v_mul_f32_e32 v161, v58, v182
	v_mul_f32_e32 v174, v42, v192
	v_mul_f32_e32 v170, v185, v61
	v_mul_f32_e32 v175, v195, v45
	v_mul_f32_e32 v171, v60, v185
	v_mul_f32_e32 v176, v44, v195
	v_fma_f32 v59, v59, v182, v160
	v_fma_f32 v43, v43, v192, v173
	v_sub_f32_e32 v58, v161, v0
	v_sub_f32_e32 v42, v174, v172
	v_fma_f32 v60, v184, v60, -v170
	v_fma_f32 v44, v194, v44, -v175
	v_fma_f32 v61, v61, v184, v171
	v_fma_f32 v45, v45, v194, v176
	v_mul_f32_e32 v0, v27, v183
	v_mul_f32_e32 v172, v11, v193
	v_mul_f32_e32 v160, v26, v183
	v_mul_f32_e32 v173, v10, v193
	v_mul_f32_e32 v161, v26, v182
	v_mul_f32_e32 v174, v10, v192
	v_mul_f32_e32 v170, v185, v29
	v_mul_f32_e32 v175, v195, v13
	v_mul_f32_e32 v171, v28, v185
	v_mul_f32_e32 v176, v12, v195
	v_fma_f32 v27, v27, v182, v160
	v_fma_f32 v11, v11, v192, v173
	v_sub_f32_e32 v26, v161, v0
	v_sub_f32_e32 v10, v174, v172
	v_fma_f32 v28, v184, v28, -v170
	v_fma_f32 v12, v194, v12, -v175
	v_fma_f32 v29, v29, v184, v171
	v_fma_f32 v13, v13, v194, v176
	s_waitcnt vmcnt(2)
	v_mul_f32_e32 v0, v55, v197
	v_mul_f32_e32 v172, v39, v205
	v_mul_f32_e32 v160, v54, v197
	v_mul_f32_e32 v173, v38, v205
	v_mul_f32_e32 v161, v54, v196
	v_mul_f32_e32 v174, v38, v204
	v_mul_f32_e32 v170, v199, v57
	v_mul_f32_e32 v175, v207, v41
	v_mul_f32_e32 v171, v56, v199
	v_mul_f32_e32 v176, v40, v207
	v_fma_f32 v55, v55, v196, v160
	v_fma_f32 v39, v39, v204, v173
	v_sub_f32_e32 v54, v161, v0
	v_sub_f32_e32 v38, v174, v172
	v_fma_f32 v56, v198, v56, -v170
	v_fma_f32 v40, v206, v40, -v175
	v_fma_f32 v57, v57, v198, v171
	v_fma_f32 v41, v41, v206, v176
	v_mul_f32_e32 v0, v23, v197
	v_mul_f32_e32 v172, v7, v205
	v_mul_f32_e32 v160, v22, v197
	v_mul_f32_e32 v173, v6, v205
	v_mul_f32_e32 v161, v22, v196
	v_mul_f32_e32 v174, v6, v204
	v_mul_f32_e32 v170, v199, v25
	v_mul_f32_e32 v175, v207, v9
	v_mul_f32_e32 v171, v24, v199
	v_mul_f32_e32 v176, v8, v207
	v_fma_f32 v23, v23, v196, v160
	v_fma_f32 v7, v7, v204, v173
	v_sub_f32_e32 v22, v161, v0
	v_sub_f32_e32 v6, v174, v172
	v_fma_f32 v24, v198, v24, -v170
	v_fma_f32 v8, v206, v8, -v175
	v_fma_f32 v25, v25, v198, v171
	v_fma_f32 v9, v9, v206, v176
	s_waitcnt vmcnt(0)
; __device__ __forceinline__ unsigned cvt_pk_bf16(float lo, float hi) { unsigned r; asm volatile("v_cvt_pk_bf16_f32 %0, %1, %2" : "=v"(r) : "v"(lo), "v"(hi)); return r; }
;     __device__ __forceinline__ void operator()(AccT& acc, const Unit& u, int wr, int wc, int fr, int fq) const {
;     ...
;                     if (rot) { const f32x4 a = v0, b = v1;
;                         v0[0] = a[0] * cs0[0] - a[1] * cs0[1]; v0[1] = a[1] * cs0[0] + a[0] * cs0[1]; v0[2] = a[2] * cs0[2] - a[3] * cs0[3]; v0[3] = a[3] * cs0[2] + a[2] * cs0[3];
;                         v1[0] = b[0] * cs1[0] - b[1] * cs1[1]; v1[1] = b[1] * cs1[0] + b[0] * cs1[1]; v1[2] = b[2] * cs1[2] - b[3] * cs1[3]; v1[3] = b[3] * cs1[2] + b[2] * cs1[3]; }
;                     u32x4 w; w.x = cvt_pk_bf16(v0[0], v0[1]); w.y = cvt_pk_bf16(v0[2], v0[3]); w.z = cvt_pk_bf16(v1[0], v1[1]); w.w = cvt_pk_bf16(v1[2], v1[3]);
;                     *(u32x4*)(rowp + bj * 128) = w; }
	v_mul_f32_e32 v0, v51, v223
	v_mul_f32_e32 v172, v35, v227
	v_mul_f32_e32 v160, v50, v223
	v_mul_f32_e32 v173, v34, v227
	v_mul_f32_e32 v161, v50, v222
	v_mul_f32_e32 v174, v34, v226
	v_mul_f32_e32 v170, v225, v53
	v_mul_f32_e32 v175, v229, v37
	v_mul_f32_e32 v171, v52, v225
	v_mul_f32_e32 v176, v36, v229
	v_fma_f32 v51, v51, v222, v160
	v_fma_f32 v35, v35, v226, v173
	v_sub_f32_e32 v50, v161, v0
	v_sub_f32_e32 v34, v174, v172
	v_fma_f32 v52, v224, v52, -v170
	v_fma_f32 v36, v228, v36, -v175
	v_fma_f32 v53, v53, v224, v171
	v_fma_f32 v37, v37, v228, v176
	v_mul_f32_e32 v0, v19, v223
	v_mul_f32_e32 v172, v3, v227
	v_mul_f32_e32 v160, v18, v223
	v_mul_f32_e32 v173, v2, v227
	v_mul_f32_e32 v161, v18, v222
	v_mul_f32_e32 v174, v2, v226
	v_mul_f32_e32 v170, v225, v21
	v_mul_f32_e32 v175, v229, v5
	v_mul_f32_e32 v171, v20, v225
	v_mul_f32_e32 v176, v4, v229
	v_fma_f32 v19, v19, v222, v160
	v_fma_f32 v3, v3, v226, v173
	v_sub_f32_e32 v18, v161, v0
	v_sub_f32_e32 v2, v174, v172
	v_fma_f32 v20, v224, v20, -v170
	v_fma_f32 v4, v228, v4, -v175
	v_fma_f32 v21, v21, v224, v171
	v_fma_f32 v5, v5, v228, v176
	v_cvt_pk_bf16_f32 v164, v126, v127
	v_cvt_pk_bf16_f32 v165, v128, v129
	v_cvt_pk_bf16_f32 v166, v110, v111
	v_cvt_pk_bf16_f32 v167, v112, v113
	global_store_dwordx4 v[142:143], v[164:167], off sc0 sc1
	v_cvt_pk_bf16_f32 v178, v94, v95
	v_cvt_pk_bf16_f32 v179, v96, v97
	v_cvt_pk_bf16_f32 v180, v78, v79
	v_cvt_pk_bf16_f32 v181, v80, v81
	global_store_dwordx4 v[142:143], v[178:181], off offset:256 sc0 sc1
	v_lshl_add_u64 v[144:145], v[142:143], 0, s[2:3]
	v_cvt_pk_bf16_f32 v164, v122, v123
	v_cvt_pk_bf16_f32 v165, v124, v125
	v_cvt_pk_bf16_f32 v166, v106, v107
	v_cvt_pk_bf16_f32 v167, v108, v109
	global_store_dwordx4 v[144:145], v[164:167], off sc0 sc1
	v_cvt_pk_bf16_f32 v178, v90, v91
	v_cvt_pk_bf16_f32 v179, v92, v93
	v_cvt_pk_bf16_f32 v180, v74, v75
	v_cvt_pk_bf16_f32 v181, v76, v77
	global_store_dwordx4 v[144:145], v[178:181], off offset:256 sc0 sc1
	v_lshl_add_u64 v[142:143], v[144:145], 0, s[2:3]
	v_cvt_pk_bf16_f32 v164, v118, v119
	v_cvt_pk_bf16_f32 v165, v120, v121
	v_cvt_pk_bf16_f32 v166, v102, v103
	v_cvt_pk_bf16_f32 v167, v104, v105
	global_store_dwordx4 v[142:143], v[164:167], off sc0 sc1
	v_cvt_pk_bf16_f32 v178, v86, v87
	v_cvt_pk_bf16_f32 v179, v88, v89
	v_cvt_pk_bf16_f32 v180, v70, v71
	v_cvt_pk_bf16_f32 v181, v72, v73
	global_store_dwordx4 v[142:143], v[178:181], off offset:256 sc0 sc1
	v_lshl_add_u64 v[144:145], v[142:143], 0, s[2:3]
	v_cvt_pk_bf16_f32 v164, v114, v115
	v_cvt_pk_bf16_f32 v165, v116, v117
	v_cvt_pk_bf16_f32 v166, v98, v99
	v_cvt_pk_bf16_f32 v167, v100, v101
	global_store_dwordx4 v[144:145], v[164:167], off sc0 sc1
	v_cvt_pk_bf16_f32 v178, v82, v83
	v_cvt_pk_bf16_f32 v179, v84, v85
	v_cvt_pk_bf16_f32 v180, v66, v67
	v_cvt_pk_bf16_f32 v181, v68, v69
	global_store_dwordx4 v[144:145], v[178:181], off offset:256 sc0 sc1
	v_lshl_add_u64 v[142:143], v[144:145], 0, s[2:3]
	v_lshl_add_u64 v[142:143], v[142:143], 0, s[2:3]
	v_lshl_add_u64 v[142:143], v[142:143], 0, s[2:3]
	v_lshl_add_u64 v[142:143], v[142:143], 0, s[2:3]
	v_lshl_add_u64 v[142:143], v[142:143], 0, s[2:3]
	v_cvt_pk_bf16_f32 v164, v62, v63
	v_cvt_pk_bf16_f32 v165, v64, v65
	v_cvt_pk_bf16_f32 v166, v46, v47
	v_cvt_pk_bf16_f32 v167, v48, v49
	global_store_dwordx4 v[142:143], v[164:167], off sc0 sc1
	v_cvt_pk_bf16_f32 v178, v30, v31
	v_cvt_pk_bf16_f32 v179, v32, v33
	v_cvt_pk_bf16_f32 v180, v14, v15
	v_cvt_pk_bf16_f32 v181, v16, v17
	global_store_dwordx4 v[142:143], v[178:181], off offset:256 sc0 sc1
	v_lshl_add_u64 v[144:145], v[142:143], 0, s[2:3]
	v_cvt_pk_bf16_f32 v164, v58, v59
	v_cvt_pk_bf16_f32 v165, v60, v61
	v_cvt_pk_bf16_f32 v166, v42, v43
	v_cvt_pk_bf16_f32 v167, v44, v45
	global_store_dwordx4 v[144:145], v[164:167], off sc0 sc1
	v_cvt_pk_bf16_f32 v178, v26, v27
	v_cvt_pk_bf16_f32 v179, v28, v29
	v_cvt_pk_bf16_f32 v180, v10, v11
	v_cvt_pk_bf16_f32 v181, v12, v13
	global_store_dwordx4 v[144:145], v[178:181], off offset:256 sc0 sc1
	v_lshl_add_u64 v[142:143], v[144:145], 0, s[2:3]
	v_cvt_pk_bf16_f32 v164, v54, v55
	v_cvt_pk_bf16_f32 v165, v56, v57
	v_cvt_pk_bf16_f32 v166, v38, v39
	v_cvt_pk_bf16_f32 v167, v40, v41
	global_store_dwordx4 v[142:143], v[164:167], off sc0 sc1
	v_cvt_pk_bf16_f32 v178, v22, v23
	v_cvt_pk_bf16_f32 v179, v24, v25
	v_cvt_pk_bf16_f32 v180, v6, v7
	v_cvt_pk_bf16_f32 v181, v8, v9
	global_store_dwordx4 v[142:143], v[178:181], off offset:256 sc0 sc1
	v_lshl_add_u64 v[144:145], v[142:143], 0, s[2:3]
	v_cvt_pk_bf16_f32 v164, v50, v51
	v_cvt_pk_bf16_f32 v165, v52, v53
	v_cvt_pk_bf16_f32 v166, v34, v35
	v_cvt_pk_bf16_f32 v167, v36, v37
	global_store_dwordx4 v[144:145], v[164:167], off sc0 sc1
	v_cvt_pk_bf16_f32 v178, v18, v19
	v_cvt_pk_bf16_f32 v179, v20, v21
	v_cvt_pk_bf16_f32 v180, v2, v3
	v_cvt_pk_bf16_f32 v181, v4, v5
	global_store_dwordx4 v[144:145], v[178:181], off offset:256 sc0 sc1
